# as v131 plus the P4a->P4b panel counter read issued right after the signal (checked before the K-loop), same byte phases
# baseline (speedup 1.0000x reference)
.LBB0_949:
	s_or_b64 exec, exec, s[4:5]
	s_mov_b64 s[4:5], s[74:75]
	s_getreg_b32 s2, hwreg(HW_REG_HW_ID, 0, 6)
	s_lshl_b32 s2, s2, 2
	s_and_b32 s2, s2, 0xfc
	s_add_i32 s2, s2, 0
	s_add_i32 s2, s2, 0x20200
	v_mov_b32_e32 v0, s2
	ds_read_b32 v0, v0
	v_mbcnt_lo_u32_b32 v1, -1, 0
	v_mbcnt_hi_u32_b32 v1, -1, v1
	s_waitcnt lgkmcnt(0)
	v_readfirstlane_b32 s2, v0
	s_lshl_b32 s2, s2, 6
	v_sub_u32_e32 v0, 0, v1
	v_cmp_eq_u32_e32 vcc, s2, v0
	s_and_saveexec_b64 s[2:3], vcc
	s_load_dwordx2 vcc, s[74:75], 0xf8
	s_waitcnt lgkmcnt(0)
	s_add_u32 vcc_lo, vcc_lo, s100
	s_addc_u32 vcc_hi, vcc_hi, 0
	v_mov_b32_e32 v139, 0x1400
	global_load_dword v138, v139, vcc sc1
	s_branch .LBB0_962
	s_nop 0

.LBB0_1029:
	v_and_b32_e32 v142, 15, v56
	v_bfe_u32 v143, v56, 4, 2
	v_or_b32_e32 v63, s16, v142
	v_lshlrev_b32_e32 v80, 4, v143
	v_lshlrev_b32_e32 v81, 6, v63
	s_movk_i32 s26, 0x3c0
	v_lshlrev_b32_e32 v63, 2, v63
	v_and_or_b32 v81, v81, s26, v80
	s_lshl_b32 s20, s20, 13
	v_and_b32_e32 v63, 32, v63
	v_lshlrev_b32_e32 v56, 2, v56
	v_bitop3_b32 v63, v81, s20, v63 bitop3:0xde
	v_lshl_or_b32 v80, v142, 6, v80
	s_lshl_b32 s20, s19, 12
	v_and_b32_e32 v56, 32, v56
	s_add_i32 m0, s22, 0x18000
	v_lshl_add_u64 v[30:31], v[30:31], 0, s[88:89]
	v_bitop3_b32 v144, v80, s20, v56 bitop3:0xde
	s_waitcnt vmcnt(2)
	s_barrier
	global_load_lds_dwordx4 v[30:31], off
	v_lshl_add_u64 v[28:29], v[28:29], 0, s[88:89]
	s_add_i32 m0, s22, 0x1a000
	s_add_i32 s20, s22, 0x8000
	global_load_lds_dwordx4 v[28:29], off
	v_lshl_add_u64 v[26:27], v[26:27], 0, s[88:89]
	s_mov_b32 m0, s20
	s_add_i32 s26, s22, 0xa000
	global_load_lds_dwordx4 v[26:27], off
	v_lshl_add_u64 v[24:25], v[24:25], 0, s[88:89]
	s_mov_b32 m0, s26
	v_readlane_b32 s28, v253, 27
	global_load_lds_dwordx4 v[24:25], off
	v_lshlrev_b32_e32 v24, 14, v57
	v_readlane_b32 s29, v253, 28
	s_add_u32 s27, s4, s28
	v_and_b32_e32 v24, 0xffff8000, v24
	s_addc_u32 s28, s5, s29
	v_readlane_b32 s29, v253, 26
	v_lshl_add_u32 v24, v58, 11, v24
	v_and_b32_e32 v25, 1, v57
	s_add_u32 s4, s4, s29
	v_readlane_b32 s29, v253, 29
	v_lshl_or_b32 v24, v25, 6, v24
	s_addc_u32 s5, s5, s29
	v_lshl_add_u32 v24, v59, 1, v24
	v_mov_b32_e32 v25, v137
	v_lshl_add_u64 v[134:135], s[4:5], 0, v[24:25]
	v_lshlrev_b32_e32 v24, 14, v60
	v_and_b32_e32 v24, 0xffff8000, v24
	v_lshl_add_u32 v24, v61, 11, v24
	v_and_b32_e32 v25, 1, v60
	v_lshl_or_b32 v24, v25, 6, v24
	v_lshl_add_u32 v24, v62, 1, v24
	v_mov_b32_e32 v25, v137
	v_lshl_add_u64 v[140:141], s[4:5], 0, v[24:25]
	v_readlane_b32 s4, v253, 31
	s_add_u32 s2, s2, s4
	v_readlane_b32 s4, v253, 32
	s_waitcnt vmcnt(4)
	s_addc_u32 s3, s3, s4
	s_add_u32 s14, s2, s14
	v_mov_b32_e32 v80, 0
	s_addc_u32 s15, s3, s15
	s_mov_b32 s29, -2
	s_mov_b64 s[2:3], 0
	s_mov_b32 s2, s101
	v_add_u32_e32 v145, 0, v63
	v_mov_b32_e32 v81, v80
	v_mov_b32_e32 v82, v80
	v_mov_b32_e32 v83, v80
	v_mov_b32_e32 v84, v80
	v_mov_b32_e32 v85, v80
	v_mov_b32_e32 v86, v80
	v_mov_b32_e32 v87, v80
	v_mov_b32_e32 v88, v80
	v_mov_b32_e32 v89, v80
	v_mov_b32_e32 v90, v80
	v_mov_b32_e32 v91, v80
	v_mov_b32_e32 v92, v80
	v_mov_b32_e32 v93, v80
	v_mov_b32_e32 v94, v80
	v_mov_b32_e32 v95, v80
	v_mov_b32_e32 v96, v80
	v_mov_b32_e32 v97, v80
	v_mov_b32_e32 v98, v80
	v_mov_b32_e32 v99, v80
	v_mov_b32_e32 v100, v80
	v_mov_b32_e32 v101, v80
	v_mov_b32_e32 v102, v80
	v_mov_b32_e32 v103, v80
	v_mov_b32_e32 v104, v80
	v_mov_b32_e32 v105, v80
	v_mov_b32_e32 v106, v80
	v_mov_b32_e32 v107, v80
	v_mov_b32_e32 v108, v80
	v_mov_b32_e32 v109, v80
	v_mov_b32_e32 v110, v80
	v_mov_b32_e32 v111, v80
	v_mov_b32_e32 v112, v80
	v_mov_b32_e32 v113, v80
	v_mov_b32_e32 v114, v80
	v_mov_b32_e32 v115, v80
	v_mov_b32_e32 v116, v80
	v_mov_b32_e32 v117, v80
	v_mov_b32_e32 v118, v80
	v_mov_b32_e32 v119, v80
	v_mov_b32_e32 v56, v80
	v_mov_b32_e32 v57, v80
	v_mov_b32_e32 v58, v80
	v_mov_b32_e32 v59, v80
	v_mov_b32_e32 v60, v80
	v_mov_b32_e32 v61, v80
	v_mov_b32_e32 v62, v80
	v_mov_b32_e32 v63, v80
	v_mov_b32_e32 v28, v80
	v_mov_b32_e32 v29, v80
	v_mov_b32_e32 v30, v80
	v_mov_b32_e32 v31, v80
	v_mov_b32_e32 v24, v80
	v_mov_b32_e32 v25, v80
	v_mov_b32_e32 v26, v80
	v_mov_b32_e32 v27, v80
	v_mov_b32_e32 v120, v80
	v_mov_b32_e32 v121, v80
	v_mov_b32_e32 v122, v80
	v_mov_b32_e32 v123, v80
	v_mov_b32_e32 v124, v80
	v_mov_b32_e32 v125, v80
	v_mov_b32_e32 v126, v80
	v_mov_b32_e32 v127, v80
	s_cmp_lg_u32 s22, 0
	s_cbranch_scc1 .Lmy_pw2_done
	s_waitcnt vmcnt(0)
	v_readfirstlane_b32 vcc_lo, v138
	s_cmp_gt_u32 vcc_lo, 7
	s_cbranch_scc1 .Lmy_pw2_ok
